# gating prologue: first head fetch issued before the LayerNorm-statistics block
# baseline (speedup 1.0000x reference)
.LBB0_503:
	s_add_i32 s0, 0, 0x23f94
	s_waitcnt vmcnt(1)
	v_mov_b32_e32 v0, s0
	s_mov_b64 s[2:3], s[90:91]
	v_mbcnt_lo_u32_b32 v52, -1, 0
	v_mbcnt_hi_u32_b32 v52, -1, v52
	ds_read_b32 v0, v0
	s_load_dwordx2 s[70:71], s[2:3], 0x48
	s_mov_b64 s[2:3], s[90:91]
	s_load_dwordx2 s[68:69], s[2:3], 0x50
	s_mov_b64 s[2:3], s[90:91]
	s_load_dwordx2 s[72:73], s[2:3], 0x58
	s_mov_b64 s[2:3], s[90:91]
	s_waitcnt lgkmcnt(0)
	v_readfirstlane_b32 s60, v0
	s_load_dwordx2 s[62:63], s[2:3], 0x60
	s_and_b32 s0, s33, 0xffffffc0
	v_add_u32_e32 v53, s0, v52
	s_lshl_b32 s0, s60, 3
	s_and_b32 s0, s0, 56
	s_ashr_i32 s64, s60, 5
	s_add_i32 s0, s0, s64
	s_movk_i32 s2, 0x80
	s_mov_b32 s1, 0
	s_lshl_b32 s0, s0, 7
	v_cmp_gt_i32_e32 vcc, s2, v53
	s_waitcnt lgkmcnt(0)
	s_barrier
	v_add_u32_e32 v150, s0, v53
	s_and_b32 s66, s60, 7
	s_mul_i32 s2, s66, 0x1400000
	s_add_u32 s2, s94, s2
	s_addc_u32 s3, s95, 0
	s_lshl_b32 s4, s66, 23
	s_sub_u32 s4, 0, s4
	v_ashrrev_i32_e32 v60, 2, v53
	s_subb_u32 s5, 0, 0
	v_and_b32_e32 v54, -2, v60
	s_add_u32 s2, s2, s4
	v_add_u32_e32 v0, s0, v54
	s_addc_u32 s3, s3, s5
	v_ashrrev_i32_e32 v1, 31, v0
	s_lshr_b32 s0, s60, 1
	v_lshlrev_b32_e32 v58, 4, v52
	v_lshlrev_b64 v[50:51], 13, v[0:1]
	s_and_b32 s4, s0, 12
	v_and_b32_e32 v59, 0x70, v58
	v_lshl_add_u64 v[0:1], s[2:3], 0, v[50:51]
	s_lshl_b32 s0, s4, 8
	v_lshl_add_u64 v[0:1], v[0:1], 0, s[0:1]
	v_lshlrev_b32_e32 v48, 1, v59
	v_mov_b32_e32 v49, 0
	v_lshl_add_u64 v[8:9], v[0:1], 0, v[48:49]
	s_mov_b32 s0, 0x13001000
	v_add_co_u32_e32 v12, vcc, s0, v8
	s_mov_b64 s[2:3], 0x13001000
	s_nop 0
	v_addc_co_u32_e32 v13, vcc, 0, v9, vcc
	s_mov_b32 s0, 0x13003000
	v_lshl_add_u64 v[10:11], v[8:9], 0, s[2:3]
	s_mov_b64 s[2:3], 0x13003000
	v_add_co_u32_e32 v18, vcc, s0, v8
	s_lshl_b32 s0, s4, 9
	v_lshl_add_u64 v[16:17], v[8:9], 0, s[2:3]
	s_add_u32 s2, s70, s0
	s_addc_u32 s3, s71, 0
	v_addc_co_u32_e32 v19, vcc, 0, v9, vcc
	v_lshlrev_b32_e32 v48, 2, v59
	s_add_u32 s4, s68, s0
	global_load_dwordx4 v[0:3], v[12:13], off
	global_load_dwordx4 v[4:7], v[10:11], off offset:16
	s_nop 0
	global_load_dwordx4 v[8:11], v[18:19], off
	global_load_dwordx4 v[12:15], v[16:17], off offset:16
	s_addc_u32 s5, s69, 0
	global_load_dwordx4 v[16:19], v48, s[2:3] offset:48
	global_load_dwordx4 v[20:23], v48, s[2:3] offset:32
	global_load_dwordx4 v[24:27], v48, s[2:3] offset:16
	global_load_dwordx4 v[28:31], v48, s[2:3]
	global_load_dwordx4 v[32:35], v48, s[4:5] offset:48
	global_load_dwordx4 v[36:39], v48, s[4:5] offset:32
	global_load_dwordx4 v[40:43], v48, s[4:5] offset:16
	global_load_dwordx4 v[44:47], v48, s[4:5]
	v_cmp_gt_i32_e32 vcc, 0x80, v53
	s_and_saveexec_b64 s[100:101], vcc
	s_cbranch_execz .Lgat_st_end
	v_ashrrev_i32_e32 v151, 31, v150
	v_lshlrev_b64 v[150:151], 8, v[150:151]
	v_lshl_add_u64 v[208:209], s[94:95], 0, v[150:151]
	s_mov_b64 s[98:99], 0x12200000
	v_add_co_u32_e32 v218, vcc, 0x12200000, v208
	v_lshl_add_u64 v[216:217], v[208:209], 0, s[98:99]
	s_nop 0
	v_addc_co_u32_e32 v219, vcc, 0, v209, vcc
	global_load_dwordx4 v[150:153], v[216:217], off offset:16
	global_load_dwordx4 v[154:157], v[216:217], off offset:32
	global_load_dwordx4 v[158:161], v[216:217], off offset:48
	global_load_dwordx4 v[162:165], v[216:217], off offset:64
	global_load_dwordx4 v[166:169], v[216:217], off offset:80
	global_load_dwordx4 v[170:173], v[216:217], off offset:96
	global_load_dwordx4 v[174:177], v[216:217], off offset:112
	global_load_dwordx4 v[178:181], v[216:217], off offset:128
	global_load_dwordx4 v[182:185], v[216:217], off offset:144
	global_load_dwordx4 v[186:189], v[216:217], off offset:160
	global_load_dwordx4 v[190:193], v[216:217], off offset:176
	global_load_dwordx4 v[194:197], v[216:217], off offset:192
	global_load_dwordx4 v[198:201], v[216:217], off offset:224
	global_load_dwordx4 v[204:207], v[216:217], off offset:208
	global_load_dwordx4 v[208:211], v[218:219], off
	global_load_dwordx4 v[212:215], v[216:217], off offset:240
	s_mov_b32 s98, 0x3a000000
	s_mov_b32 s99, 0xf800000
	s_waitcnt vmcnt(15)
	v_add_f32_e32 v150, v150, v152
	s_waitcnt vmcnt(14)
	v_add_f32_e32 v152, v154, v156
	v_add_f32_e32 v151, v151, v153
	s_waitcnt vmcnt(12)
	v_add_f32_e32 v156, v162, v164
	v_add_f32_e32 v153, v155, v157
	v_add_f32_e32 v157, v163, v165
	v_add_f32_e32 v154, v158, v160
	s_waitcnt vmcnt(8)
	v_add_f32_e32 v164, v178, v180
	v_add_f32_e32 v165, v179, v181
	v_add_f32_e32 v155, v159, v161
	v_add_f32_e32 v158, v166, v168
	s_waitcnt vmcnt(1)
	v_add_f32_e32 v178, v208, v210
	v_add_f32_e32 v178, 0, v178
	v_add_f32_e32 v179, v209, v211
	v_add_f32_e32 v150, v178, v150
	v_add_f32_e32 v179, 0, v179
	v_add_f32_e32 v150, v150, v152
	v_add_f32_e32 v151, v179, v151
	v_add_f32_e32 v150, v150, v154
	v_add_f32_e32 v151, v151, v153
	v_add_f32_e32 v150, v150, v156
	v_add_f32_e32 v160, v170, v172
	v_add_f32_e32 v151, v151, v155
	v_add_f32_e32 v150, v150, v158
	v_add_f32_e32 v159, v167, v169
	v_add_f32_e32 v162, v174, v176
	v_add_f32_e32 v151, v151, v157
	v_add_f32_e32 v150, v150, v160
	v_add_f32_e32 v161, v171, v173
	v_add_f32_e32 v151, v151, v159
	v_add_f32_e32 v150, v150, v162
	v_add_f32_e32 v163, v175, v177
	v_add_f32_e32 v166, v182, v184
	v_add_f32_e32 v151, v151, v161
	v_add_f32_e32 v150, v150, v164
	v_add_f32_e32 v168, v186, v188
	v_add_f32_e32 v151, v151, v163
	v_add_f32_e32 v150, v150, v166
	v_add_f32_e32 v167, v183, v185
	v_add_f32_e32 v170, v190, v192
	v_add_f32_e32 v151, v151, v165
	v_add_f32_e32 v150, v150, v168
	v_add_f32_e32 v169, v187, v189
	v_add_f32_e32 v172, v194, v196
	v_add_f32_e32 v151, v151, v167
	v_add_f32_e32 v150, v150, v170
	v_add_f32_e32 v171, v191, v193
	v_add_f32_e32 v174, v204, v206
	v_add_f32_e32 v151, v151, v169
	v_add_f32_e32 v150, v150, v172
	v_add_f32_e32 v173, v195, v197
	v_add_f32_e32 v176, v198, v200
	v_add_f32_e32 v151, v151, v171
	v_add_f32_e32 v150, v150, v174
	v_add_f32_e32 v175, v205, v207
	s_waitcnt vmcnt(0)
	v_add_f32_e32 v180, v212, v214
	v_add_f32_e32 v151, v151, v173
	v_add_f32_e32 v150, v150, v176
	v_add_f32_e32 v177, v199, v201
	v_add_f32_e32 v151, v151, v175
	v_add_f32_e32 v150, v150, v180
	v_add_f32_e32 v181, v213, v215
	v_add_f32_e32 v151, v151, v177
	v_mul_f32_e32 v150, 0x3a000000, v150
	v_add_f32_e32 v151, v151, v181
	v_mul_f32_e32 v152, v150, v150
	v_fma_f32 v151, v151, s98, -v152
	v_add_f32_e32 v151, 0x358637bd, v151
	v_mul_f32_e32 v152, 0x4f800000, v151
	v_cmp_gt_f32_e32 vcc, s99, v151
	v_mov_b32_e32 v154, 0x260
	v_lshl_add_u32 v153, v53, 2, 0
	v_cndmask_b32_e32 v151, v151, v152, vcc
	v_sqrt_f32_e32 v152, v151
	v_add_u32_e32 v153, 0x11000, v153
	v_add_u32_e32 v155, -1, v152
	v_add_u32_e32 v156, 1, v152
	v_fma_f32 v157, -v155, v152, v151
	v_fma_f32 v158, -v156, v152, v151
	v_cmp_ge_f32_e64 s[98:99], 0, v157
	s_nop 1
	v_cndmask_b32_e64 v152, v152, v155, s[98:99]
	v_cmp_lt_f32_e64 s[98:99], 0, v158
	s_nop 1
	v_cndmask_b32_e64 v152, v152, v156, s[98:99]
	v_mul_f32_e32 v155, 0x37800000, v152
	v_cndmask_b32_e32 v152, v152, v155, vcc
	v_cmp_class_f32_e32 vcc, v151, v154
	s_nop 1
	v_cndmask_b32_e32 v151, v152, v151, vcc
	v_div_scale_f32 v152, s[98:99], v151, v151, 1.0
	v_rcp_f32_e32 v154, v152
	v_div_scale_f32 v155, vcc, 1.0, v151, 1.0
	v_fma_f32 v156, -v152, v154, 1.0
	v_fmac_f32_e32 v154, v156, v154
	v_mul_f32_e32 v156, v155, v154
	v_fma_f32 v157, -v152, v156, v155
	v_fmac_f32_e32 v156, v157, v154
	v_fma_f32 v152, -v152, v156, v155
	v_div_fmas_f32 v152, v152, v154, v156
	v_div_fixup_f32 v151, v152, v151, 1.0
	ds_write2st64_b32 v153, v150, v151 offset1:2
.Lgat_st_end:
	s_or_b64 exec, exec, s[100:101]
	s_add_i32 s0, 0, 0x11000
	v_lshl_add_u32 v48, v54, 2, s0
	v_bitop3_b32 v53, v53, -4, 4 bitop3:0xc8
	v_ashrrev_i32_e32 v56, 4, v52
	s_waitcnt lgkmcnt(0)
	s_barrier
	v_add_u32_e32 v53, s0, v53
	ds_read_b32 v124, v48
	ds_read_b64 v[92:93], v48 offset:512
	ds_read_b32 v125, v53
	v_and_b32_e32 v48, 48, v58
	v_and_b32_e32 v62, 15, v52
	s_lshl_b32 s0, s88, 4
	v_lshlrev_b32_e32 v54, 3, v56
	v_bitop3_b32 v48, v60, v48, -2 bitop3:0x6c
	v_or_b32_e32 v53, s0, v62
	v_lshlrev_b32_e32 v127, 1, v48
	v_or_b32_e32 v48, 2, v54
	v_cmp_gt_i32_e64 s[6:7], v48, v53
	v_or_b32_e32 v48, 3, v54
	v_cmp_gt_i32_e64 s[8:9], v48, v53
	v_or_b32_e32 v48, 4, v54
	v_cmp_gt_i32_e64 s[10:11], v48, v53
	v_or_b32_e32 v48, 5, v54
	v_cmp_gt_i32_e64 s[12:13], v48, v53
	v_or_b32_e32 v48, 6, v54
	v_cmp_gt_i32_e64 s[14:15], v48, v53
	v_or_b32_e32 v48, 7, v54
	v_cmp_gt_i32_e64 s[16:17], v48, v53
	v_add_u32_e32 v48, 32, v54
	v_cmp_gt_i32_e64 s[18:19], v48, v53
	v_add_u32_e32 v48, 33, v54
	v_cmp_gt_i32_e64 s[20:21], v48, v53
	v_add_u32_e32 v48, 34, v54
	v_cmp_gt_i32_e64 s[22:23], v48, v53
	v_add_u32_e32 v48, 35, v54
	v_cmp_gt_i32_e64 s[24:25], v48, v53
	v_add_u32_e32 v48, 36, v54
	v_cmp_gt_i32_e64 s[26:27], v48, v53
	v_add_u32_e32 v48, 37, v54
	v_cmp_gt_i32_e64 s[28:29], v48, v53
	v_add_u32_e32 v48, 38, v54
	v_cmp_gt_i32_e64 s[30:31], v48, v53
	v_add_u32_e32 v48, 39, v54
	v_cmp_gt_i32_e64 s[34:35], v48, v53
	v_add_u32_e32 v48, 64, v54
	v_cmp_gt_i32_e64 s[36:37], v48, v53
	v_add_u32_e32 v48, 0x41, v54
	v_cmp_gt_i32_e64 s[38:39], v48, v53
	v_add_u32_e32 v48, 0x42, v54
	v_cmp_gt_i32_e64 s[40:41], v48, v53
	v_add_u32_e32 v48, 0x43, v54
	v_cmp_gt_i32_e64 s[42:43], v48, v53
	v_add_u32_e32 v48, 0x44, v54
	v_cmp_gt_i32_e64 s[44:45], v48, v53
	v_add_u32_e32 v48, 0x45, v54
	s_cmpk_gt_u32 s33, 0x7f
	v_cmp_gt_i32_e64 s[46:47], v48, v53
	v_add_u32_e32 v48, 0x46, v54
	s_cselect_b64 s[76:77], -1, 0
	s_cmpk_gt_u32 s33, 0xff
	v_cmp_gt_i32_e64 s[48:49], v48, v53
	v_add_u32_e32 v48, 0x47, v54
	s_cselect_b64 s[78:79], -1, 0
	s_cmpk_gt_u32 s33, 0x17f
	v_cmp_gt_i32_e64 s[50:51], v48, v53
	v_add_u32_e32 v48, 0x60, v54
	s_cselect_b64 s[80:81], -1, 0
	v_cmp_gt_i32_e64 s[52:53], v48, v53
	v_add_u32_e32 v48, 0x61, v54
	s_bfe_u32 s82, s60, 0x20003
	v_cmp_gt_i32_e64 s[54:55], v48, v53
	v_add_u32_e32 v48, 0x62, v54
	s_lshl_b32 s60, s82, 9
	v_cmp_gt_i32_e64 s[56:57], v48, v53
	v_add_u32_e32 v48, 0x63, v54
	s_add_i32 s60, s60, s0
	v_cmp_gt_i32_e64 s[58:59], v48, v53
	v_or_b32_e32 v48, s60, v62
	v_lshl_add_u64 v[94:95], v[48:49], 2, s[62:63]
	s_lshl_b32 s62, s66, 10
	s_lshl_b32 s63, s64, 7
	v_add_u32_e32 v58, 0x64, v54
	s_add_i32 s64, s62, s63
	v_cmp_gt_i32_e64 s[60:61], v58, v53
	v_add_u32_e32 v58, 0x65, v54
	s_add_i32 s64, s64, s0
	v_cmp_gt_i32_e64 s[62:63], v58, v53
	v_or_b32_e32 v58, s64, v62
	v_lshlrev_b32_e32 v56, 2, v56
	v_mul_u32_u24_e32 v126, 0x110, v59
	v_ashrrev_i32_e32 v59, 31, v58
	v_ashrrev_i32_e32 v57, 31, v56
	s_lshl_b32 s64, s66, 24
	s_mov_b32 s65, s1
	v_lshlrev_b64 v[60:61], 12, v[58:59]
	v_lshl_add_u64 v[60:61], s[64:65], 0, v[60:61]
	v_lshlrev_b64 v[56:57], 1, v[56:57]
	v_lshl_add_u64 v[60:61], v[60:61], 0, v[56:57]
	v_lshl_add_u64 v[60:61], s[94:95], 0, v[60:61]
	s_mov_b64 s[64:65], 0x13800080
	s_movk_i32 s67, 0x60
	v_lshl_add_u64 v[96:97], v[60:61], 0, s[64:65]
	v_lshlrev_b64 v[58:59], 13, v[58:59]
	v_mov_b32_e32 v60, 0xc00000
	v_mad_u64_u32 v[58:59], s[64:65], s66, v60, v[58:59]
	v_bitop3_b32 v128, v52, s67, -16 bitop3:0x6c
	v_mad_u64_u32 v[50:51], s[66:67], s66, v60, v[50:51]
	v_and_b32_e32 v130, -16, v52
	v_bitop3_b32 v131, v52, 32, -16 bitop3:0x6c
	v_bitop3_b32 v132, v52, 64, -16 bitop3:0x6c
	v_and_b32_e32 v52, 7, v52
	v_lshl_add_u64 v[56:57], v[58:59], 0, v[56:57]
	v_lshl_or_b32 v50, v52, 5, v50
	v_ashrrev_i32_e32 v55, 31, v54
	v_lshl_add_u64 v[56:57], s[94:95], 0, v[56:57]
	s_mov_b64 s[64:65], 0x13000080
	v_lshl_add_u64 v[100:101], s[94:95], 0, v[50:51]
	v_mov_b32_e32 v51, v49
	v_lshlrev_b64 v[48:49], 9, v[48:49]
	v_add_u32_e32 v63, 0x66, v54
	v_lshl_add_u64 v[98:99], v[56:57], 0, s[64:65]
	v_add_u32_e32 v56, 0x67, v54
	v_lshlrev_b32_e32 v50, 6, v52
	v_lshl_add_u64 v[48:49], v[54:55], 2, v[48:49]
	v_cmp_gt_i32_e64 s[2:3], v54, v53
	v_cmp_lt_i32_e64 s[4:5], v54, v53
	v_cmp_gt_i32_e64 s[64:65], v63, v53
	v_cmp_gt_i32_e64 s[66:67], v56, v53
	v_add_u32_e32 v53, 64, v130
	v_add_u32_e32 v56, 0xc0, v130
	s_lshl_b32 s0, s82, 10
	v_lshl_or_b32 v50, s82, 11, v50
	v_lshl_add_u64 v[48:49], s[72:73], 0, v[48:49]
	s_mov_b64 s[82:83], 0x100
	s_mov_b64 s[74:75], 0
	s_mov_b32 s96, s88
	v_mul_u32_u24_e32 v129, 0x110, v62
	v_xor_b32_e32 v133, 64, v53
	v_xor_b32_e32 v134, 64, v56
	v_xor_b32_e32 v135, 0x60, v53
	v_xor_b32_e32 v136, 0x60, v56
	v_lshl_add_u64 v[102:103], s[70:71], 0, v[50:51]
	v_lshl_add_u64 v[104:105], v[48:49], 0, s[82:83]
	v_lshl_add_u64 v[106:107], s[68:69], 0, v[50:51]
	s_mov_b32 s84, 0xffff0000
	s_movk_i32 s85, 0x7fff
	s_mov_b32 s88, s1
	s_branch .LBB0_507
